# v_m11 + attn_scan l0h0: the 128 weight-conversion items are handed out first instead of last (longest-first queue order)
# speedup vs baseline: 1.0035x; 1.0035x over previous
; DI int otid() { int t; asm volatile("v_mov_b32 %0, %1" : "=v"(t) : "v"((int)threadIdx.x)); return t; }
; DI void phase_attn_scan(const Params& p, int l, int half, char* smem, int rep) {
;     ...
;   unsigned* cnt = p.cnt + (l * 2 + half) + 8 * rep;
;   for (;;) {
;     __syncthreads();
;     if (threadIdx.x == 0) s_item = (int)atomicAdd(cnt, 1u);
;     __syncthreads();
;     int it = s_item;
;     if (it >= total) break;
;     if (it < n_scan) { scan_item(p, it, smem); continue; }
;     it -= n_scan;
;     if (it >= n_lat + n_ctx + n_gate) { conv_layer(p, 1, (long)(it - n_lat - n_ctx - n_gate) * 256 + otid(), (long)n_conv * 256); continue; }
.LBB0_161:
	s_or_b64 exec, exec, s[12:13]
	s_waitcnt vmcnt(0)
	v_readfirstlane_b32 s12, v1
	s_nop 1
	v_add_u32_e32 v0, s12, v0
	s_add_i32 s21, s12, 0x80
	s_cmp_eq_u32 s69, 0xfe0
	s_cbranch_scc0 .Lq_noconv
	s_add_i32 s21, s12, 0xf60
	s_cmpk_lt_u32 s12, 0x80
	s_cbranch_scc1 .Lq_noconv
	s_mov_b32 s21, s12
	s_cmpk_lt_u32 s12, 0xf60
	s_cbranch_scc1 .Lq_noconv
	s_movk_i32 s21, 0x1000
.Lq_noconv:
	v_mov_b32_e32 v0, s21
	v_cmp_le_i32_e32 vcc, s69, v0
	s_cbranch_vccz .Lq_store
	v_readlane_b32 s36, v255, 23
	v_readlane_b32 s37, v255, 24
	v_mov_b32_e32 v1, 1
	s_nop 4
	global_atomic_add v1, v177, v1, s[36:37] offset:128 sc0
	s_waitcnt vmcnt(0)
	v_cmp_gt_u32_e32 vcc, 0x80, v1
	s_nop 1
	v_cndmask_b32_e32 v0, v0, v1, vcc
